# speedup vs baseline: 1.0018x; 1.0018x over previous
.LBB0_369:
	ds_read_b128 v[176:179], v228
	ds_read_b128 v[180:183], v228 offset:2048
	s_and_b32 s22, s23, 3
	v_lshl_add_u32 v84, s22, 13, v229
	v_add_u32_e32 v86, v84, v230
	v_add_u32_e32 v87, v84, v231
	ds_read_b128 v[160:163], v86
	ds_read_b128 v[164:167], v87
	ds_read_b128 v[184:187], v228 offset:1024
	ds_read_b128 v[188:191], v228 offset:3072
	ds_read_b128 v[168:171], v86 offset:512
	ds_read_b128 v[172:175], v87 offset:512
	ds_read_b128 v[140:143], v86 offset:4096
	ds_read_b128 v[144:147], v87 offset:4096
	v_cvt_pk_bf16_f32 v120, v241, v244
	v_cvt_pk_bf16_f32 v121, v245, v247
	v_cvt_pk_bf16_f32 v122, v240, v242
	v_cvt_pk_bf16_f32 v123, v243, v246
	v_cvt_pk_bf16_f32 v112, v153, v156
	v_cvt_pk_bf16_f32 v113, v158, v159
	v_cvt_pk_bf16_f32 v114, v152, v154
	v_cvt_pk_bf16_f32 v115, v155, v157
	v_cvt_pk_bf16_f32 v124, v137, v148
	v_cvt_pk_bf16_f32 v125, v149, v151
	v_cvt_pk_bf16_f32 v126, v132, v136
	v_cvt_pk_bf16_f32 v127, v139, v150
	v_cvt_pk_bf16_f32 v116, v129, v134
	v_cvt_pk_bf16_f32 v117, v135, v138
	v_cvt_pk_bf16_f32 v118, v128, v130
	v_cvt_pk_bf16_f32 v119, v131, v133
	s_andn2_b64 vcc, exec, s[6:7]
	s_cbranch_vccz .Lh1a_resc
.Lh1a_resc_ret:
	s_mov_b32 s82, s80
	s_mov_b32 s83, s80
	s_mov_b32 s81, s80
	v_mov_b64_e32 v[154:155], s[82:83]
	v_mov_b64_e32 v[152:153], s[80:81]
	s_and_b32 s0, s19, 0xc000
	v_add_u32_e32 v212, s0, v223
	v_add_u32_e32 v213, s0, v224
	v_mfma_f32_16x16x32_bf16 v[68:71], v[120:123], v[152:155], v[68:71]
	v_mfma_f32_16x16x32_bf16 v[56:59], v[124:127], v[152:155], v[56:59]
	v_mfma_f32_16x16x32_bf16 v[68:71], v[112:115], v[152:155], v[68:71]
	v_mfma_f32_16x16x32_bf16 v[56:59], v[116:119], v[152:155], v[56:59]
	s_add_i32 s21, s23, 2
	s_min_i32 s12, s21, 0xff
	s_mul_i32 s0, s12, 0xc0000
	s_add_u32 s0, s86, s0
	s_addc_u32 s1, s87, 0
	s_and_b32 s12, s12, 3
	s_lshl_b32 s13, s12, 13
	s_lshl_b32 s12, s12, 14
	s_add_i32 s12, s18, s12
	ds_read_b128 v[240:243], v86 offset:4608
	ds_read_b128 v[244:247], v87 offset:4608
	s_waitcnt lgkmcnt(6)
	ds_read_b64_tr_b16 v[128:129], v212
	ds_read_b64_tr_b16 v[130:131], v212 offset:4096
	ds_read_b64_tr_b16 v[132:133], v212 offset:8192
	ds_read_b64_tr_b16 v[134:135], v212 offset:12288
	v_mfma_f32_16x16x32_bf16 v[84:87], v[160:163], v[176:179], v[72:75]
	v_mfma_f32_16x16x32_bf16 v[80:83], v[160:163], v[180:183], v[76:79]
	v_mfma_f32_16x16x32_bf16 v[84:87], v[164:167], v[184:187], v[84:87]
	v_mfma_f32_16x16x32_bf16 v[80:83], v[164:167], v[188:191], v[80:83]
	s_add_i32 m0, s17, s13
	s_nop 0
	global_load_lds_dwordx4 v232, s[0:1]
	s_waitcnt lgkmcnt(8)
	ds_read_b64_tr_b16 v[136:137], v213
	ds_read_b64_tr_b16 v[138:139], v213 offset:4096
	ds_read_b64_tr_b16 v[148:149], v213 offset:8192
	ds_read_b64_tr_b16 v[150:151], v213 offset:12288
	v_mfma_f32_16x16x32_bf16 v[96:99], v[168:171], v[176:179], v[72:75]
	v_mfma_f32_16x16x32_bf16 v[88:91], v[168:171], v[180:183], v[76:79]
	v_mfma_f32_16x16x32_bf16 v[96:99], v[172:175], v[184:187], v[96:99]
	v_mfma_f32_16x16x32_bf16 v[88:91], v[172:175], v[188:191], v[88:91]
	s_mov_b32 m0, s12
	s_nop 0
	global_load_lds_dwordx4 v233, s[0:1]
	s_waitcnt lgkmcnt(10)
	ds_read_b64_tr_b16 v[152:153], v212 offset:1024
	ds_read_b64_tr_b16 v[154:155], v212 offset:5120
	ds_read_b64_tr_b16 v[156:157], v212 offset:9216
	ds_read_b64_tr_b16 v[158:159], v212 offset:13312
	v_mfma_f32_16x16x32_bf16 v[100:103], v[140:143], v[176:179], v[72:75]
	v_mfma_f32_16x16x32_bf16 v[92:95], v[140:143], v[180:183], v[76:79]
	v_mfma_f32_16x16x32_bf16 v[100:103], v[144:147], v[184:187], v[100:103]
	v_mfma_f32_16x16x32_bf16 v[92:95], v[144:147], v[188:191], v[92:95]
	s_add_i32 m0, s12, 0x2000
	s_nop 0
	global_load_lds_dwordx4 v234, s[0:1]
	s_waitcnt lgkmcnt(12)
	v_mfma_f32_16x16x32_bf16 v[108:111], v[240:243], v[176:179], v[72:75]
	v_mfma_f32_16x16x32_bf16 v[104:107], v[240:243], v[180:183], v[76:79]
	v_mfma_f32_16x16x32_bf16 v[108:111], v[244:247], v[184:187], v[108:111]
	v_mfma_f32_16x16x32_bf16 v[104:107], v[244:247], v[188:191], v[104:107]
	s_cmp_le_i32 s23, s75
	s_cbranch_scc0 .LBB0_379

; DEV void diff16_pass(const bf16_t* __restrict__ proj, int qcol, int kcol, int vcol, int q0, f32x4 (&o)[2][8], f32x4 (&l_out)[2], unsigned char* lds) {
;     ...
;   for (int j = 1; j < NT; j += 2) {
;     HALF16(SB2, alB, rfB, SA, alA, rfA, j);
;     if (j + 1 >= NT) break;
;     HALF16(SA, alA, rfA, SB2, alB, rfB, j + 1);
.LBB0_373:
	s_waitcnt lgkmcnt(8)
	ds_read_b64_tr_b16 v[240:241], v212 offset:2048
	ds_read_b64_tr_b16 v[242:243], v212 offset:6144
	ds_read_b64_tr_b16 v[244:245], v212 offset:10240
	ds_read_b64_tr_b16 v[246:247], v212 offset:14336
	v_mfma_f32_16x16x32_bf16 v[52:55], v[120:123], v[136:139], v[52:55]
	v_exp_f32_e32 v162, v84
	v_mfma_f32_16x16x32_bf16 v[48:51], v[124:127], v[136:139], v[48:51]
	v_exp_f32_e32 v163, v85
	v_mfma_f32_16x16x32_bf16 v[52:55], v[112:115], v[148:151], v[52:55]
	v_exp_f32_e32 v161, v86
	v_mfma_f32_16x16x32_bf16 v[48:51], v[116:119], v[148:151], v[48:51]
	v_exp_f32_e32 v160, v87
	v_exp_f32_e32 v167, v96
	s_waitcnt lgkmcnt(8)
	ds_read_b64_tr_b16 v[128:129], v213 offset:2048
	ds_read_b64_tr_b16 v[130:131], v213 offset:6144
	ds_read_b64_tr_b16 v[132:133], v213 offset:10240
	ds_read_b64_tr_b16 v[134:135], v213 offset:14336
	v_mfma_f32_16x16x32_bf16 v[44:47], v[120:123], v[152:155], v[44:47]
	v_exp_f32_e32 v166, v97
	v_mfma_f32_16x16x32_bf16 v[40:43], v[124:127], v[152:155], v[40:43]
	v_exp_f32_e32 v164, v98
	v_mfma_f32_16x16x32_bf16 v[44:47], v[112:115], v[156:159], v[44:47]
	v_exp_f32_e32 v165, v99
	v_mfma_f32_16x16x32_bf16 v[40:43], v[116:119], v[156:159], v[40:43]
	v_exp_f32_e32 v171, v100
	v_exp_f32_e32 v170, v101
	s_waitcnt lgkmcnt(8)
	ds_read_b64_tr_b16 v[136:137], v212 offset:3072
	ds_read_b64_tr_b16 v[138:139], v212 offset:7168
	ds_read_b64_tr_b16 v[148:149], v212 offset:11264
	ds_read_b64_tr_b16 v[150:151], v212 offset:15360
	v_mfma_f32_16x16x32_bf16 v[32:35], v[120:123], v[140:143], v[32:35]
	v_exp_f32_e32 v169, v102
	v_mfma_f32_16x16x32_bf16 v[36:39], v[124:127], v[140:143], v[36:39]
	v_exp_f32_e32 v168, v103
	v_mfma_f32_16x16x32_bf16 v[32:35], v[112:115], v[144:147], v[32:35]
	v_exp_f32_e32 v178, v108
	v_mfma_f32_16x16x32_bf16 v[36:39], v[116:119], v[144:147], v[36:39]
	v_exp_f32_e32 v179, v109
	v_exp_f32_e32 v177, v110
	s_waitcnt lgkmcnt(8)
	ds_read_b64_tr_b16 v[152:153], v213 offset:3072
	ds_read_b64_tr_b16 v[154:155], v213 offset:7168
	ds_read_b64_tr_b16 v[156:157], v213 offset:11264
	ds_read_b64_tr_b16 v[158:159], v213 offset:15360
	v_mfma_f32_16x16x32_bf16 v[20:23], v[120:123], v[240:243], v[20:23]
	v_exp_f32_e32 v176, v111
	v_mfma_f32_16x16x32_bf16 v[16:19], v[124:127], v[240:243], v[16:19]
	v_exp_f32_e32 v175, v80
	v_mfma_f32_16x16x32_bf16 v[20:23], v[112:115], v[244:247], v[20:23]
	v_exp_f32_e32 v174, v81
	v_mfma_f32_16x16x32_bf16 v[16:19], v[116:119], v[244:247], v[16:19]
	v_exp_f32_e32 v172, v82
	v_exp_f32_e32 v173, v83
	s_waitcnt lgkmcnt(8)
	v_mfma_f32_16x16x32_bf16 v[28:31], v[120:123], v[128:131], v[28:31]
	v_exp_f32_e32 v183, v88
	v_mfma_f32_16x16x32_bf16 v[24:27], v[124:127], v[128:131], v[24:27]
	v_exp_f32_e32 v182, v89
	v_mfma_f32_16x16x32_bf16 v[28:31], v[112:115], v[132:135], v[28:31]
	v_exp_f32_e32 v181, v90
	v_mfma_f32_16x16x32_bf16 v[24:27], v[116:119], v[132:135], v[24:27]
	v_exp_f32_e32 v180, v91
	s_waitcnt lgkmcnt(4)
	v_mfma_f32_16x16x32_bf16 v[12:15], v[120:123], v[136:139], v[12:15]
	v_exp_f32_e32 v186, v92
	v_mfma_f32_16x16x32_bf16 v[8:11], v[124:127], v[136:139], v[8:11]
	v_exp_f32_e32 v187, v93
	v_mfma_f32_16x16x32_bf16 v[12:15], v[112:115], v[148:151], v[12:15]
	v_exp_f32_e32 v185, v94
	v_mfma_f32_16x16x32_bf16 v[8:11], v[116:119], v[148:151], v[8:11]
	v_exp_f32_e32 v184, v95
	s_add_i32 s0, s23, 1
	s_cmp_ge_i32 s0, s14
	s_mov_b64 s[0:1], -1
	s_waitcnt lgkmcnt(0)
	v_mfma_f32_16x16x32_bf16 v[4:7], v[120:123], v[152:155], v[4:7]
	v_exp_f32_e32 v191, v104
	v_mfma_f32_16x16x32_bf16 v[0:3], v[124:127], v[152:155], v[0:3]
	v_exp_f32_e32 v190, v105
	v_mfma_f32_16x16x32_bf16 v[4:7], v[112:115], v[156:159], v[4:7]
	v_exp_f32_e32 v189, v106
	v_mfma_f32_16x16x32_bf16 v[0:3], v[116:119], v[156:159], v[0:3]
	v_exp_f32_e32 v188, v107
	s_waitcnt vmcnt(3)
	s_waitcnt lgkmcnt(0)
	s_barrier
	s_cbranch_scc1 .LBB0_368
	ds_read_b128 v[240:243], v228
	ds_read_b128 v[244:247], v228 offset:2048
	s_and_b32 s0, s20, 0x6000
	v_add_u32_e32 v84, s0, v229
	v_add_u32_e32 v86, v84, v230
	v_add_u32_e32 v87, v84, v231
	ds_read_b128 v[128:131], v86
	ds_read_b128 v[132:135], v87
	ds_read_b128 v[152:155], v228 offset:1024
	ds_read_b128 v[156:159], v228 offset:3072
	ds_read_b128 v[136:139], v86 offset:512
	ds_read_b128 v[148:151], v87 offset:512
	ds_read_b128 v[140:143], v86 offset:4096
	ds_read_b128 v[144:147], v87 offset:4096
	v_cvt_pk_bf16_f32 v120, v162, v163
	v_cvt_pk_bf16_f32 v121, v161, v160
	v_cvt_pk_bf16_f32 v122, v167, v166
	v_cvt_pk_bf16_f32 v123, v164, v165
	v_cvt_pk_bf16_f32 v112, v171, v170
	v_cvt_pk_bf16_f32 v113, v169, v168
	v_cvt_pk_bf16_f32 v114, v178, v179
	v_cvt_pk_bf16_f32 v115, v177, v176
	v_cvt_pk_bf16_f32 v124, v175, v174
	v_cvt_pk_bf16_f32 v125, v172, v173
	v_cvt_pk_bf16_f32 v126, v183, v182
	v_cvt_pk_bf16_f32 v127, v181, v180
	v_cvt_pk_bf16_f32 v116, v186, v187
	v_cvt_pk_bf16_f32 v117, v185, v184
	v_cvt_pk_bf16_f32 v118, v191, v190
	v_cvt_pk_bf16_f32 v119, v189, v188
	s_andn2_b64 vcc, exec, s[12:13]
	s_cbranch_vccz .Lh2a_resc
.Lh2a_resc_ret:
	s_mov_b32 s82, s80
	s_mov_b32 s83, s80
	s_mov_b32 s81, s80
	v_mov_b64_e32 v[186:187], s[82:83]
	v_mov_b64_e32 v[184:185], s[80:81]
	s_lshl_b32 s0, s22, 14
	v_add_u32_e32 v214, s0, v223
	v_add_u32_e32 v215, s0, v224
	v_mfma_f32_16x16x32_bf16 v[68:71], v[120:123], v[184:187], v[68:71]
	v_mfma_f32_16x16x32_bf16 v[56:59], v[124:127], v[184:187], v[56:59]
	v_mfma_f32_16x16x32_bf16 v[68:71], v[112:115], v[184:187], v[68:71]
	v_mfma_f32_16x16x32_bf16 v[56:59], v[116:119], v[184:187], v[56:59]
	s_min_i32 s0, s23, 0xfc
	s_add_i32 s6, s0, 3
	s_mul_i32 s0, s6, 0xc0000
	s_add_u32 s0, s86, s0
	s_addc_u32 s1, s87, 0
	s_and_b32 s6, s6, 3
	s_lshl_b32 s7, s6, 13
	s_lshl_b32 s6, s6, 14
	s_add_i32 s6, s18, s6
	ds_read_b128 v[160:163], v86 offset:4608
	ds_read_b128 v[164:167], v87 offset:4608
	s_waitcnt lgkmcnt(6)
	ds_read_b64_tr_b16 v[168:169], v214
	ds_read_b64_tr_b16 v[170:171], v214 offset:4096
	ds_read_b64_tr_b16 v[172:173], v214 offset:8192
	ds_read_b64_tr_b16 v[174:175], v214 offset:12288
	v_mfma_f32_16x16x32_bf16 v[84:87], v[128:131], v[240:243], v[72:75]
	v_mfma_f32_16x16x32_bf16 v[80:83], v[128:131], v[244:247], v[76:79]
	v_mfma_f32_16x16x32_bf16 v[84:87], v[132:135], v[152:155], v[84:87]
	v_mfma_f32_16x16x32_bf16 v[80:83], v[132:135], v[156:159], v[80:83]
	s_add_i32 m0, s17, s7
	s_nop 0
	global_load_lds_dwordx4 v232, s[0:1]
	s_waitcnt lgkmcnt(8)
	ds_read_b64_tr_b16 v[176:177], v215
	ds_read_b64_tr_b16 v[178:179], v215 offset:4096
	ds_read_b64_tr_b16 v[180:181], v215 offset:8192
	ds_read_b64_tr_b16 v[182:183], v215 offset:12288
	v_mfma_f32_16x16x32_bf16 v[96:99], v[136:139], v[240:243], v[72:75]
	v_mfma_f32_16x16x32_bf16 v[88:91], v[136:139], v[244:247], v[76:79]
	v_mfma_f32_16x16x32_bf16 v[96:99], v[148:151], v[152:155], v[96:99]
	v_mfma_f32_16x16x32_bf16 v[88:91], v[148:151], v[156:159], v[88:91]
	s_mov_b32 m0, s6
	s_nop 0
	global_load_lds_dwordx4 v233, s[0:1]
	s_waitcnt lgkmcnt(10)
	ds_read_b64_tr_b16 v[184:185], v214 offset:1024
	ds_read_b64_tr_b16 v[186:187], v214 offset:5120
	ds_read_b64_tr_b16 v[188:189], v214 offset:9216
	ds_read_b64_tr_b16 v[190:191], v214 offset:13312
	v_mfma_f32_16x16x32_bf16 v[100:103], v[140:143], v[240:243], v[72:75]
	v_mfma_f32_16x16x32_bf16 v[92:95], v[140:143], v[244:247], v[76:79]
	v_mfma_f32_16x16x32_bf16 v[100:103], v[144:147], v[152:155], v[100:103]
	v_mfma_f32_16x16x32_bf16 v[92:95], v[144:147], v[156:159], v[92:95]
	s_add_i32 m0, s6, 0x2000
	s_nop 0
	global_load_lds_dwordx4 v234, s[0:1]
	s_waitcnt lgkmcnt(12)
	v_mfma_f32_16x16x32_bf16 v[108:111], v[160:163], v[240:243], v[72:75]
	v_mfma_f32_16x16x32_bf16 v[104:107], v[160:163], v[244:247], v[76:79]
	v_mfma_f32_16x16x32_bf16 v[108:111], v[164:167], v[152:155], v[108:111]
	v_mfma_f32_16x16x32_bf16 v[104:107], v[164:167], v[156:159], v[104:107]
	s_cmp_lt_i32 s23, s75
	s_cbranch_scc0 .LBB0_384

; DEV void diff16_pass(const bf16_t* __restrict__ proj, int qcol, int kcol, int vcol, int q0, f32x4 (&o)[2][8], f32x4 (&l_out)[2], unsigned char* lds) {
;     ...
;   for (int j = 1; j < NT; j += 2) {
;     HALF16(SB2, alB, rfB, SA, alA, rfA, j);
;     if (j + 1 >= NT) break;
;     HALF16(SA, alA, rfA, SB2, alB, rfB, j + 1);
.LBB0_390:
	s_waitcnt lgkmcnt(8)
	ds_read_b64_tr_b16 v[160:161], v214 offset:2048
	ds_read_b64_tr_b16 v[162:163], v214 offset:6144
	ds_read_b64_tr_b16 v[164:165], v214 offset:10240
	ds_read_b64_tr_b16 v[166:167], v214 offset:14336
	v_mfma_f32_16x16x32_bf16 v[52:55], v[120:123], v[176:179], v[52:55]
	v_exp_f32_e32 v241, v84
	v_mfma_f32_16x16x32_bf16 v[48:51], v[124:127], v[176:179], v[48:51]
	v_exp_f32_e32 v244, v85
	v_mfma_f32_16x16x32_bf16 v[52:55], v[112:115], v[180:183], v[52:55]
	v_exp_f32_e32 v245, v86
	v_mfma_f32_16x16x32_bf16 v[48:51], v[116:119], v[180:183], v[48:51]
	v_exp_f32_e32 v247, v87
	v_exp_f32_e32 v240, v96
	s_waitcnt lgkmcnt(8)
	ds_read_b64_tr_b16 v[168:169], v215 offset:2048
	ds_read_b64_tr_b16 v[170:171], v215 offset:6144
	ds_read_b64_tr_b16 v[172:173], v215 offset:10240
	ds_read_b64_tr_b16 v[174:175], v215 offset:14336
	v_mfma_f32_16x16x32_bf16 v[44:47], v[120:123], v[184:187], v[44:47]
	v_exp_f32_e32 v242, v97
	v_mfma_f32_16x16x32_bf16 v[40:43], v[124:127], v[184:187], v[40:43]
	v_exp_f32_e32 v243, v98
	v_mfma_f32_16x16x32_bf16 v[44:47], v[112:115], v[188:191], v[44:47]
	v_exp_f32_e32 v246, v99
	v_mfma_f32_16x16x32_bf16 v[40:43], v[116:119], v[188:191], v[40:43]
	v_exp_f32_e32 v137, v80
	v_exp_f32_e32 v148, v81
	s_waitcnt lgkmcnt(8)
	ds_read_b64_tr_b16 v[176:177], v214 offset:3072
	ds_read_b64_tr_b16 v[178:179], v214 offset:7168
	ds_read_b64_tr_b16 v[180:181], v214 offset:11264
	ds_read_b64_tr_b16 v[182:183], v214 offset:15360
	v_mfma_f32_16x16x32_bf16 v[32:35], v[120:123], v[140:143], v[32:35]
	v_exp_f32_e32 v149, v82
	v_mfma_f32_16x16x32_bf16 v[36:39], v[124:127], v[140:143], v[36:39]
	v_exp_f32_e32 v151, v83
	v_mfma_f32_16x16x32_bf16 v[32:35], v[112:115], v[144:147], v[32:35]
	v_exp_f32_e32 v136, v89
	v_mfma_f32_16x16x32_bf16 v[36:39], v[116:119], v[144:147], v[36:39]
	v_exp_f32_e32 v139, v90
	v_exp_f32_e32 v150, v91
	s_waitcnt lgkmcnt(8)
	ds_read_b64_tr_b16 v[184:185], v215 offset:3072
	ds_read_b64_tr_b16 v[186:187], v215 offset:7168
	ds_read_b64_tr_b16 v[188:189], v215 offset:11264
	ds_read_b64_tr_b16 v[190:191], v215 offset:15360
	v_mfma_f32_16x16x32_bf16 v[20:23], v[120:123], v[160:163], v[20:23]
	v_exp_f32_e32 v129, v92
	v_mfma_f32_16x16x32_bf16 v[16:19], v[124:127], v[160:163], v[16:19]
	v_exp_f32_e32 v138, v95
	v_mfma_f32_16x16x32_bf16 v[20:23], v[112:115], v[164:167], v[20:23]
	v_exp_f32_e32 v128, v104
	v_mfma_f32_16x16x32_bf16 v[16:19], v[116:119], v[164:167], v[16:19]
	v_exp_f32_e32 v130, v105
	v_exp_f32_e32 v131, v106
	s_waitcnt lgkmcnt(8)
	v_mfma_f32_16x16x32_bf16 v[28:31], v[120:123], v[168:171], v[28:31]
	v_exp_f32_e32 v153, v100
	v_mfma_f32_16x16x32_bf16 v[24:27], v[124:127], v[168:171], v[24:27]
	v_exp_f32_e32 v152, v108
	v_mfma_f32_16x16x32_bf16 v[28:31], v[112:115], v[172:175], v[28:31]
	v_exp_f32_e32 v154, v109
	v_mfma_f32_16x16x32_bf16 v[24:27], v[116:119], v[172:175], v[24:27]
	v_exp_f32_e32 v155, v110
	s_waitcnt lgkmcnt(4)
	v_mfma_f32_16x16x32_bf16 v[12:15], v[120:123], v[176:179], v[12:15]
	v_exp_f32_e32 v156, v101
	v_mfma_f32_16x16x32_bf16 v[8:11], v[124:127], v[176:179], v[8:11]
	v_exp_f32_e32 v158, v102
	v_mfma_f32_16x16x32_bf16 v[12:15], v[112:115], v[180:183], v[12:15]
	v_exp_f32_e32 v159, v103
	v_mfma_f32_16x16x32_bf16 v[8:11], v[116:119], v[180:183], v[8:11]
	v_exp_f32_e32 v157, v111
	s_add_i32 s19, s19, 0x8000
	s_addk_i32 s20, 0x4000
	s_cmp_ge_i32 s21, s14
	s_cselect_b64 s[0:1], -1, 0
	s_and_b64 vcc, exec, s[0:1]
	s_mov_b32 s23, s21
	s_waitcnt lgkmcnt(0)
	v_mfma_f32_16x16x32_bf16 v[4:7], v[120:123], v[184:187], v[4:7]
	v_exp_f32_e32 v132, v88
	v_mfma_f32_16x16x32_bf16 v[0:3], v[124:127], v[184:187], v[0:3]
	v_exp_f32_e32 v134, v93
	v_mfma_f32_16x16x32_bf16 v[4:7], v[112:115], v[188:191], v[4:7]
	v_exp_f32_e32 v135, v94
	v_mfma_f32_16x16x32_bf16 v[0:3], v[116:119], v[188:191], v[0:3]
	v_exp_f32_e32 v133, v107
	s_waitcnt vmcnt(3)
	s_waitcnt lgkmcnt(0)
	s_barrier
	s_cbranch_vccz .LBB0_369
	s_branch .LBB0_392

.LBB0_396:
	ds_read_b128 v[176:179], v228
	ds_read_b128 v[180:183], v228 offset:2048
	s_and_b32 s18, s19, 3
	v_lshl_add_u32 v84, s18, 13, v229
	v_add_u32_e32 v86, v84, v230
	v_add_u32_e32 v87, v84, v231
	ds_read_b128 v[160:163], v86
	ds_read_b128 v[164:167], v87
	ds_read_b128 v[184:187], v228 offset:1024
	ds_read_b128 v[188:191], v228 offset:3072
	ds_read_b128 v[168:171], v86 offset:512
	ds_read_b128 v[172:175], v87 offset:512
	ds_read_b128 v[140:143], v86 offset:4096
	ds_read_b128 v[144:147], v87 offset:4096
	v_cvt_pk_bf16_f32 v120, v241, v244
	v_cvt_pk_bf16_f32 v121, v245, v247
	v_cvt_pk_bf16_f32 v122, v240, v242
	v_cvt_pk_bf16_f32 v123, v243, v246
	v_cvt_pk_bf16_f32 v112, v153, v156
	v_cvt_pk_bf16_f32 v113, v158, v159
	v_cvt_pk_bf16_f32 v114, v152, v154
	v_cvt_pk_bf16_f32 v115, v155, v157
	v_cvt_pk_bf16_f32 v124, v137, v148
	v_cvt_pk_bf16_f32 v125, v149, v151
	v_cvt_pk_bf16_f32 v126, v132, v136
	v_cvt_pk_bf16_f32 v127, v139, v150
	v_cvt_pk_bf16_f32 v116, v129, v134
	v_cvt_pk_bf16_f32 v117, v135, v138
	v_cvt_pk_bf16_f32 v118, v128, v130
	v_cvt_pk_bf16_f32 v119, v131, v133
	s_andn2_b64 vcc, exec, s[6:7]
	s_cbranch_vccz .Lh1b_resc
.Lh1b_resc_ret:
	s_mov_b32 s82, s80
	s_mov_b32 s83, s80
	s_mov_b32 s81, s80
	v_mov_b64_e32 v[154:155], s[82:83]
	v_mov_b64_e32 v[152:153], s[80:81]
	s_and_b32 s0, s15, 0xc000
	v_add_u32_e32 v212, s0, v223
	v_add_u32_e32 v213, s0, v224
	v_mfma_f32_16x16x32_bf16 v[68:71], v[120:123], v[152:155], v[68:71]
	v_mfma_f32_16x16x32_bf16 v[56:59], v[124:127], v[152:155], v[56:59]
	v_mfma_f32_16x16x32_bf16 v[68:71], v[112:115], v[152:155], v[68:71]
	v_mfma_f32_16x16x32_bf16 v[56:59], v[116:119], v[152:155], v[56:59]
	s_add_i32 s17, s19, 2
	s_min_i32 s10, s17, 0xff
	s_mul_i32 s0, s10, 0xc0000
	s_add_u32 s0, s86, s0
	s_addc_u32 s1, s87, 0
	s_and_b32 s10, s10, 3
	s_lshl_b32 s11, s10, 13
	s_lshl_b32 s10, s10, 14
	s_add_i32 s10, s13, s10
	ds_read_b128 v[240:243], v86 offset:4608
	ds_read_b128 v[244:247], v87 offset:4608
	s_waitcnt lgkmcnt(6)
	ds_read_b64_tr_b16 v[128:129], v212
	ds_read_b64_tr_b16 v[130:131], v212 offset:4096
	ds_read_b64_tr_b16 v[132:133], v212 offset:8192
	ds_read_b64_tr_b16 v[134:135], v212 offset:12288
	v_mfma_f32_16x16x32_bf16 v[84:87], v[160:163], v[176:179], v[72:75]
	v_mfma_f32_16x16x32_bf16 v[80:83], v[160:163], v[180:183], v[76:79]
	v_mfma_f32_16x16x32_bf16 v[84:87], v[164:167], v[184:187], v[84:87]
	v_mfma_f32_16x16x32_bf16 v[80:83], v[164:167], v[188:191], v[80:83]
	s_add_i32 m0, s12, s11
	s_nop 0
	global_load_lds_dwordx4 v232, s[0:1]
	s_waitcnt lgkmcnt(8)
	ds_read_b64_tr_b16 v[136:137], v213
	ds_read_b64_tr_b16 v[138:139], v213 offset:4096
	ds_read_b64_tr_b16 v[148:149], v213 offset:8192
	ds_read_b64_tr_b16 v[150:151], v213 offset:12288
	v_mfma_f32_16x16x32_bf16 v[96:99], v[168:171], v[176:179], v[72:75]
	v_mfma_f32_16x16x32_bf16 v[88:91], v[168:171], v[180:183], v[76:79]
	v_mfma_f32_16x16x32_bf16 v[96:99], v[172:175], v[184:187], v[96:99]
	v_mfma_f32_16x16x32_bf16 v[88:91], v[172:175], v[188:191], v[88:91]
	s_mov_b32 m0, s10
	s_nop 0
	global_load_lds_dwordx4 v233, s[0:1]
	s_waitcnt lgkmcnt(10)
	ds_read_b64_tr_b16 v[152:153], v212 offset:1024
	ds_read_b64_tr_b16 v[154:155], v212 offset:5120
	ds_read_b64_tr_b16 v[156:157], v212 offset:9216
	ds_read_b64_tr_b16 v[158:159], v212 offset:13312
	v_mfma_f32_16x16x32_bf16 v[100:103], v[140:143], v[176:179], v[72:75]
	v_mfma_f32_16x16x32_bf16 v[92:95], v[140:143], v[180:183], v[76:79]
	v_mfma_f32_16x16x32_bf16 v[100:103], v[144:147], v[184:187], v[100:103]
	v_mfma_f32_16x16x32_bf16 v[92:95], v[144:147], v[188:191], v[92:95]
	s_add_i32 m0, s10, 0x2000
	s_nop 0
	global_load_lds_dwordx4 v234, s[0:1]
	s_waitcnt lgkmcnt(12)
	v_mfma_f32_16x16x32_bf16 v[108:111], v[240:243], v[176:179], v[72:75]
	v_mfma_f32_16x16x32_bf16 v[104:107], v[240:243], v[180:183], v[76:79]
	v_mfma_f32_16x16x32_bf16 v[108:111], v[244:247], v[184:187], v[108:111]
	v_mfma_f32_16x16x32_bf16 v[104:107], v[244:247], v[188:191], v[104:107]
	s_cmp_le_i32 s19, s75
	s_cbranch_scc0 .LBB0_406

; DEV void diff16_pass(const bf16_t* __restrict__ proj, int qcol, int kcol, int vcol, int q0, f32x4 (&o)[2][8], f32x4 (&l_out)[2], unsigned char* lds) {
;     ...
;   for (int j = 1; j < NT; j += 2) {
;     HALF16(SB2, alB, rfB, SA, alA, rfA, j);
;     if (j + 1 >= NT) break;
;     HALF16(SA, alA, rfA, SB2, alB, rfB, j + 1);
.LBB0_400:
	s_waitcnt lgkmcnt(8)
	ds_read_b64_tr_b16 v[240:241], v212 offset:2048
	ds_read_b64_tr_b16 v[242:243], v212 offset:6144
	ds_read_b64_tr_b16 v[244:245], v212 offset:10240
	ds_read_b64_tr_b16 v[246:247], v212 offset:14336
	v_mfma_f32_16x16x32_bf16 v[52:55], v[120:123], v[136:139], v[52:55]
	v_exp_f32_e32 v162, v84
	v_mfma_f32_16x16x32_bf16 v[48:51], v[124:127], v[136:139], v[48:51]
	v_exp_f32_e32 v163, v85
	v_mfma_f32_16x16x32_bf16 v[52:55], v[112:115], v[148:151], v[52:55]
	v_exp_f32_e32 v161, v86
	v_mfma_f32_16x16x32_bf16 v[48:51], v[116:119], v[148:151], v[48:51]
	v_exp_f32_e32 v160, v87
	v_exp_f32_e32 v167, v96
	s_waitcnt lgkmcnt(8)
	ds_read_b64_tr_b16 v[128:129], v213 offset:2048
	ds_read_b64_tr_b16 v[130:131], v213 offset:6144
	ds_read_b64_tr_b16 v[132:133], v213 offset:10240
	ds_read_b64_tr_b16 v[134:135], v213 offset:14336
	v_mfma_f32_16x16x32_bf16 v[44:47], v[120:123], v[152:155], v[44:47]
	v_exp_f32_e32 v166, v97
	v_mfma_f32_16x16x32_bf16 v[40:43], v[124:127], v[152:155], v[40:43]
	v_exp_f32_e32 v164, v98
	v_mfma_f32_16x16x32_bf16 v[44:47], v[112:115], v[156:159], v[44:47]
	v_exp_f32_e32 v165, v99
	v_mfma_f32_16x16x32_bf16 v[40:43], v[116:119], v[156:159], v[40:43]
	v_exp_f32_e32 v171, v100
	v_exp_f32_e32 v170, v101
	s_waitcnt lgkmcnt(8)
	ds_read_b64_tr_b16 v[136:137], v212 offset:3072
	ds_read_b64_tr_b16 v[138:139], v212 offset:7168
	ds_read_b64_tr_b16 v[148:149], v212 offset:11264
	ds_read_b64_tr_b16 v[150:151], v212 offset:15360
	v_mfma_f32_16x16x32_bf16 v[32:35], v[120:123], v[140:143], v[32:35]
	v_exp_f32_e32 v169, v102
	v_mfma_f32_16x16x32_bf16 v[36:39], v[124:127], v[140:143], v[36:39]
	v_exp_f32_e32 v168, v103
	v_mfma_f32_16x16x32_bf16 v[32:35], v[112:115], v[144:147], v[32:35]
	v_exp_f32_e32 v178, v108
	v_mfma_f32_16x16x32_bf16 v[36:39], v[116:119], v[144:147], v[36:39]
	v_exp_f32_e32 v179, v109
	v_exp_f32_e32 v177, v110
	s_waitcnt lgkmcnt(8)
	ds_read_b64_tr_b16 v[152:153], v213 offset:3072
	ds_read_b64_tr_b16 v[154:155], v213 offset:7168
	ds_read_b64_tr_b16 v[156:157], v213 offset:11264
	ds_read_b64_tr_b16 v[158:159], v213 offset:15360
	v_mfma_f32_16x16x32_bf16 v[20:23], v[120:123], v[240:243], v[20:23]
	v_exp_f32_e32 v176, v111
	v_mfma_f32_16x16x32_bf16 v[16:19], v[124:127], v[240:243], v[16:19]
	v_exp_f32_e32 v175, v80
	v_mfma_f32_16x16x32_bf16 v[20:23], v[112:115], v[244:247], v[20:23]
	v_exp_f32_e32 v174, v81
	v_mfma_f32_16x16x32_bf16 v[16:19], v[116:119], v[244:247], v[16:19]
	v_exp_f32_e32 v172, v82
	v_exp_f32_e32 v173, v83
	s_waitcnt lgkmcnt(8)
	v_mfma_f32_16x16x32_bf16 v[28:31], v[120:123], v[128:131], v[28:31]
	v_exp_f32_e32 v183, v88
	v_mfma_f32_16x16x32_bf16 v[24:27], v[124:127], v[128:131], v[24:27]
	v_exp_f32_e32 v182, v89
	v_mfma_f32_16x16x32_bf16 v[28:31], v[112:115], v[132:135], v[28:31]
	v_exp_f32_e32 v181, v90
	v_mfma_f32_16x16x32_bf16 v[24:27], v[116:119], v[132:135], v[24:27]
	v_exp_f32_e32 v180, v91
	s_waitcnt lgkmcnt(4)
	v_mfma_f32_16x16x32_bf16 v[12:15], v[120:123], v[136:139], v[12:15]
	v_exp_f32_e32 v186, v92
	v_mfma_f32_16x16x32_bf16 v[8:11], v[124:127], v[136:139], v[8:11]
	v_exp_f32_e32 v187, v93
	v_mfma_f32_16x16x32_bf16 v[12:15], v[112:115], v[148:151], v[12:15]
	v_exp_f32_e32 v185, v94
	v_mfma_f32_16x16x32_bf16 v[8:11], v[116:119], v[148:151], v[8:11]
	v_exp_f32_e32 v184, v95
	s_add_i32 s0, s19, 1
	s_cmp_ge_i32 s0, s14
	s_mov_b64 s[0:1], -1
	s_waitcnt lgkmcnt(0)
	v_mfma_f32_16x16x32_bf16 v[4:7], v[120:123], v[152:155], v[4:7]
	v_exp_f32_e32 v191, v104
	v_mfma_f32_16x16x32_bf16 v[0:3], v[124:127], v[152:155], v[0:3]
	v_exp_f32_e32 v190, v105
	v_mfma_f32_16x16x32_bf16 v[4:7], v[112:115], v[156:159], v[4:7]
	v_exp_f32_e32 v189, v106
	v_mfma_f32_16x16x32_bf16 v[0:3], v[116:119], v[156:159], v[0:3]
	v_exp_f32_e32 v188, v107
	s_waitcnt vmcnt(3)
	s_waitcnt lgkmcnt(0)
	s_barrier
	s_cbranch_scc1 .LBB0_395
	ds_read_b128 v[240:243], v228
	ds_read_b128 v[244:247], v228 offset:2048
	s_and_b32 s0, s16, 0x6000
	v_add_u32_e32 v84, s0, v229
	v_add_u32_e32 v86, v84, v230
	v_add_u32_e32 v87, v84, v231
	ds_read_b128 v[128:131], v86
	ds_read_b128 v[132:135], v87
	ds_read_b128 v[152:155], v228 offset:1024
	ds_read_b128 v[156:159], v228 offset:3072
	ds_read_b128 v[136:139], v86 offset:512
	ds_read_b128 v[148:151], v87 offset:512
	ds_read_b128 v[140:143], v86 offset:4096
	ds_read_b128 v[144:147], v87 offset:4096
	v_cvt_pk_bf16_f32 v120, v162, v163
	v_cvt_pk_bf16_f32 v121, v161, v160
	v_cvt_pk_bf16_f32 v122, v167, v166
	v_cvt_pk_bf16_f32 v123, v164, v165
	v_cvt_pk_bf16_f32 v112, v171, v170
	v_cvt_pk_bf16_f32 v113, v169, v168
	v_cvt_pk_bf16_f32 v114, v178, v179
	v_cvt_pk_bf16_f32 v115, v177, v176
	v_cvt_pk_bf16_f32 v124, v175, v174
	v_cvt_pk_bf16_f32 v125, v172, v173
	v_cvt_pk_bf16_f32 v126, v183, v182
	v_cvt_pk_bf16_f32 v127, v181, v180
	v_cvt_pk_bf16_f32 v116, v186, v187
	v_cvt_pk_bf16_f32 v117, v185, v184
	v_cvt_pk_bf16_f32 v118, v191, v190
	v_cvt_pk_bf16_f32 v119, v189, v188
	s_andn2_b64 vcc, exec, s[10:11]
	s_cbranch_vccz .Lh2b_resc
.Lh2b_resc_ret:
	s_mov_b32 s82, s80
	s_mov_b32 s83, s80
	s_mov_b32 s81, s80
	v_mov_b64_e32 v[186:187], s[82:83]
	v_mov_b64_e32 v[184:185], s[80:81]
	s_lshl_b32 s0, s18, 14
	v_add_u32_e32 v214, s0, v223
	v_add_u32_e32 v215, s0, v224
	v_mfma_f32_16x16x32_bf16 v[68:71], v[120:123], v[184:187], v[68:71]
	v_mfma_f32_16x16x32_bf16 v[56:59], v[124:127], v[184:187], v[56:59]
	v_mfma_f32_16x16x32_bf16 v[68:71], v[112:115], v[184:187], v[68:71]
	v_mfma_f32_16x16x32_bf16 v[56:59], v[116:119], v[184:187], v[56:59]
	s_min_i32 s0, s19, 0xfc
	s_add_i32 s6, s0, 3
	s_mul_i32 s0, s6, 0xc0000
	s_add_u32 s0, s86, s0
	s_addc_u32 s1, s87, 0
	s_and_b32 s6, s6, 3
	s_lshl_b32 s7, s6, 13
	s_lshl_b32 s6, s6, 14
	s_add_i32 s6, s13, s6
	ds_read_b128 v[160:163], v86 offset:4608
	ds_read_b128 v[164:167], v87 offset:4608
	s_waitcnt lgkmcnt(6)
	ds_read_b64_tr_b16 v[168:169], v214
	ds_read_b64_tr_b16 v[170:171], v214 offset:4096
	ds_read_b64_tr_b16 v[172:173], v214 offset:8192
	ds_read_b64_tr_b16 v[174:175], v214 offset:12288
	v_mfma_f32_16x16x32_bf16 v[84:87], v[128:131], v[240:243], v[72:75]
	v_mfma_f32_16x16x32_bf16 v[80:83], v[128:131], v[244:247], v[76:79]
	v_mfma_f32_16x16x32_bf16 v[84:87], v[132:135], v[152:155], v[84:87]
	v_mfma_f32_16x16x32_bf16 v[80:83], v[132:135], v[156:159], v[80:83]
	s_add_i32 m0, s12, s7
	s_nop 0
	global_load_lds_dwordx4 v232, s[0:1]
	s_waitcnt lgkmcnt(8)
	ds_read_b64_tr_b16 v[176:177], v215
	ds_read_b64_tr_b16 v[178:179], v215 offset:4096
	ds_read_b64_tr_b16 v[180:181], v215 offset:8192
	ds_read_b64_tr_b16 v[182:183], v215 offset:12288
	v_mfma_f32_16x16x32_bf16 v[96:99], v[136:139], v[240:243], v[72:75]
	v_mfma_f32_16x16x32_bf16 v[88:91], v[136:139], v[244:247], v[76:79]
	v_mfma_f32_16x16x32_bf16 v[96:99], v[148:151], v[152:155], v[96:99]
	v_mfma_f32_16x16x32_bf16 v[88:91], v[148:151], v[156:159], v[88:91]
	s_mov_b32 m0, s6
	s_nop 0
	global_load_lds_dwordx4 v233, s[0:1]
	s_waitcnt lgkmcnt(10)
	ds_read_b64_tr_b16 v[184:185], v214 offset:1024
	ds_read_b64_tr_b16 v[186:187], v214 offset:5120
	ds_read_b64_tr_b16 v[188:189], v214 offset:9216
	ds_read_b64_tr_b16 v[190:191], v214 offset:13312
	v_mfma_f32_16x16x32_bf16 v[100:103], v[140:143], v[240:243], v[72:75]
	v_mfma_f32_16x16x32_bf16 v[92:95], v[140:143], v[244:247], v[76:79]
	v_mfma_f32_16x16x32_bf16 v[100:103], v[144:147], v[152:155], v[100:103]
	v_mfma_f32_16x16x32_bf16 v[92:95], v[144:147], v[156:159], v[92:95]
	s_add_i32 m0, s6, 0x2000
	s_nop 0
	global_load_lds_dwordx4 v234, s[0:1]
	s_waitcnt lgkmcnt(12)
	v_mfma_f32_16x16x32_bf16 v[108:111], v[160:163], v[240:243], v[72:75]
	v_mfma_f32_16x16x32_bf16 v[104:107], v[160:163], v[244:247], v[76:79]
	v_mfma_f32_16x16x32_bf16 v[108:111], v[164:167], v[152:155], v[108:111]
	v_mfma_f32_16x16x32_bf16 v[104:107], v[164:167], v[156:159], v[104:107]
	s_cmp_lt_i32 s19, s75
	s_cbranch_scc0 .LBB0_411

; DEV void diff16_pass(const bf16_t* __restrict__ proj, int qcol, int kcol, int vcol, int q0, f32x4 (&o)[2][8], f32x4 (&l_out)[2], unsigned char* lds) {
;     ...
;   for (int j = 1; j < NT; j += 2) {
;     HALF16(SB2, alB, rfB, SA, alA, rfA, j);
;     if (j + 1 >= NT) break;
;     HALF16(SA, alA, rfA, SB2, alB, rfB, j + 1);
.LBB0_417:
	s_waitcnt lgkmcnt(8)
	ds_read_b64_tr_b16 v[160:161], v214 offset:2048
	ds_read_b64_tr_b16 v[162:163], v214 offset:6144
	ds_read_b64_tr_b16 v[164:165], v214 offset:10240
	ds_read_b64_tr_b16 v[166:167], v214 offset:14336
	v_mfma_f32_16x16x32_bf16 v[52:55], v[120:123], v[176:179], v[52:55]
	v_exp_f32_e32 v241, v84
	v_mfma_f32_16x16x32_bf16 v[48:51], v[124:127], v[176:179], v[48:51]
	v_exp_f32_e32 v244, v85
	v_mfma_f32_16x16x32_bf16 v[52:55], v[112:115], v[180:183], v[52:55]
	v_exp_f32_e32 v245, v86
	v_mfma_f32_16x16x32_bf16 v[48:51], v[116:119], v[180:183], v[48:51]
	v_exp_f32_e32 v247, v87
	v_exp_f32_e32 v240, v96
	s_waitcnt lgkmcnt(8)
	ds_read_b64_tr_b16 v[168:169], v215 offset:2048
	ds_read_b64_tr_b16 v[170:171], v215 offset:6144
	ds_read_b64_tr_b16 v[172:173], v215 offset:10240
	ds_read_b64_tr_b16 v[174:175], v215 offset:14336
	v_mfma_f32_16x16x32_bf16 v[44:47], v[120:123], v[184:187], v[44:47]
	v_exp_f32_e32 v242, v97
	v_mfma_f32_16x16x32_bf16 v[40:43], v[124:127], v[184:187], v[40:43]
	v_exp_f32_e32 v243, v98
	v_mfma_f32_16x16x32_bf16 v[44:47], v[112:115], v[188:191], v[44:47]
	v_exp_f32_e32 v246, v99
	v_mfma_f32_16x16x32_bf16 v[40:43], v[116:119], v[188:191], v[40:43]
	v_exp_f32_e32 v137, v80
	v_exp_f32_e32 v148, v81
	s_waitcnt lgkmcnt(8)
	ds_read_b64_tr_b16 v[176:177], v214 offset:3072
	ds_read_b64_tr_b16 v[178:179], v214 offset:7168
	ds_read_b64_tr_b16 v[180:181], v214 offset:11264
	ds_read_b64_tr_b16 v[182:183], v214 offset:15360
	v_mfma_f32_16x16x32_bf16 v[32:35], v[120:123], v[140:143], v[32:35]
	v_exp_f32_e32 v149, v82
	v_mfma_f32_16x16x32_bf16 v[36:39], v[124:127], v[140:143], v[36:39]
	v_exp_f32_e32 v151, v83
	v_mfma_f32_16x16x32_bf16 v[32:35], v[112:115], v[144:147], v[32:35]
	v_exp_f32_e32 v136, v89
	v_mfma_f32_16x16x32_bf16 v[36:39], v[116:119], v[144:147], v[36:39]
	v_exp_f32_e32 v139, v90
	v_exp_f32_e32 v150, v91
	s_waitcnt lgkmcnt(8)
	ds_read_b64_tr_b16 v[184:185], v215 offset:3072
	ds_read_b64_tr_b16 v[186:187], v215 offset:7168
	ds_read_b64_tr_b16 v[188:189], v215 offset:11264
	ds_read_b64_tr_b16 v[190:191], v215 offset:15360
	v_mfma_f32_16x16x32_bf16 v[20:23], v[120:123], v[160:163], v[20:23]
	v_exp_f32_e32 v129, v92
	v_mfma_f32_16x16x32_bf16 v[16:19], v[124:127], v[160:163], v[16:19]
	v_exp_f32_e32 v138, v95
	v_mfma_f32_16x16x32_bf16 v[20:23], v[112:115], v[164:167], v[20:23]
	v_exp_f32_e32 v128, v104
	v_mfma_f32_16x16x32_bf16 v[16:19], v[116:119], v[164:167], v[16:19]
	v_exp_f32_e32 v130, v105
	v_exp_f32_e32 v131, v106
	s_waitcnt lgkmcnt(8)
	v_mfma_f32_16x16x32_bf16 v[28:31], v[120:123], v[168:171], v[28:31]
	v_exp_f32_e32 v153, v100
	v_mfma_f32_16x16x32_bf16 v[24:27], v[124:127], v[168:171], v[24:27]
	v_exp_f32_e32 v152, v108
	v_mfma_f32_16x16x32_bf16 v[28:31], v[112:115], v[172:175], v[28:31]
	v_exp_f32_e32 v154, v109
	v_mfma_f32_16x16x32_bf16 v[24:27], v[116:119], v[172:175], v[24:27]
	v_exp_f32_e32 v155, v110
	s_waitcnt lgkmcnt(4)
	v_mfma_f32_16x16x32_bf16 v[12:15], v[120:123], v[176:179], v[12:15]
	v_exp_f32_e32 v156, v101
	v_mfma_f32_16x16x32_bf16 v[8:11], v[124:127], v[176:179], v[8:11]
	v_exp_f32_e32 v158, v102
	v_mfma_f32_16x16x32_bf16 v[12:15], v[112:115], v[180:183], v[12:15]
	v_exp_f32_e32 v159, v103
	v_mfma_f32_16x16x32_bf16 v[8:11], v[116:119], v[180:183], v[8:11]
	v_exp_f32_e32 v157, v111
	s_add_i32 s15, s15, 0x8000
	s_addk_i32 s16, 0x4000
	s_cmp_ge_i32 s17, s14
	s_cselect_b64 s[0:1], -1, 0
	s_and_b64 vcc, exec, s[0:1]
	s_mov_b32 s19, s17
	s_waitcnt lgkmcnt(0)
	v_mfma_f32_16x16x32_bf16 v[4:7], v[120:123], v[184:187], v[4:7]
	v_exp_f32_e32 v132, v88
	v_mfma_f32_16x16x32_bf16 v[0:3], v[124:127], v[184:187], v[0:3]
	v_exp_f32_e32 v134, v93
	v_mfma_f32_16x16x32_bf16 v[4:7], v[112:115], v[188:191], v[4:7]
	v_exp_f32_e32 v135, v94
	v_mfma_f32_16x16x32_bf16 v[0:3], v[116:119], v[188:191], v[0:3]
	v_exp_f32_e32 v133, v107
	s_waitcnt vmcnt(3)
	s_waitcnt lgkmcnt(0)
	s_barrier
	s_cbranch_vccz .LBB0_396
	s_branch .LBB0_419
